# v30 plus the two loop-invariant LDS read-address VALU adds hoisted out of the in-projection GEMM K-loop (loader wave now issues no VALU in the loop)
# speedup vs baseline: 1.0015x; 1.0009x over previous
; #define PG8_STAGE(bufoff, gbase, voff) do { _Pragma("unroll") for (int _i = 0; _i < 2; ++_i) \
;         __builtin_amdgcn_global_load_lds((const unsigned*)((const char*)(gbase) + (voff)[_i]), (LAS unsigned*)(lds + (bufoff) + ldsw + _i * 8192), 16, 0, 0); } while (0)
; #define PG8_LDA(dst, b, h) do { _Pragma("unroll") for (int m = 0; m < 4; ++m) _Pragma("unroll") for (int k = 0; k < 2; ++k) dst[m][k] = *(const LAS bf16x8*)(lds + PG8_SA(b, h) + aoff + m * 2048 + k * 1024); } while (0)
; #define PG8_SCHED __builtin_amdgcn_sched_barrier(0)
; template <class Epi, class Sched, bool ALIGN_EPI = false, bool SP2 = false, bool TWOA = false, bool AGM = false>
; __device__ __forceinline__ void gemm_phase(LAS unsigned char* lds, const Gemm g, const Sched& S, const Epi& E, int wid) {
;     ...
; #pragma unroll
;     for (int a = 0; a < 2; ++a)
; #pragma unroll
;         for (int b = 0; b < 2; ++b)
; #pragma unroll
;             for (int m = 0; m < 4; ++m)
; #pragma unroll
;                 for (int n = 0; n < 2; ++n) acc[a][b][m][n] = (f32x4){0.f, 0.f, 0.f, 0.f};
;     ...
;         const bool has_next = S.next(ui + 1, nxt);
;         const char* nA = has_next ? (const char*)g.A + (size_t)nxt.pm * tstepA : cA; const char* nB = has_next ? (const char*)g.Bt + (size_t)nxt.pn * tstep : cB;
;         for (int t = 0; t < nt; t += 2) {
;             const bool last = (t == nt - 2);
;             const char* cA2 = TWOA ? (const char*)g.A2 + (cA - (const char*)g.A) - (size_t)nh * kstepA : cA;
;             const char* a1_ = (TWOA && t + 1 >= nh ? cA2 : cA) + (size_t)(t + 1) * kstepA;
;             const char* a2_ = last ? nA : (TWOA && t + 2 >= nh ? cA2 : cA) + (size_t)(t + 2) * kstepA; const char* a1 = a1_; const char* a2 = a2_; const char* b2 = last ? nB : cB + (size_t)(t + 2) * kstep;
;             if constexpr (TWOA) { asm volatile("" : "+s"(a1)); asm volatile("" : "+s"(a2)); }
;             const char* a3 = a2 + kstepA; const char* b3 = b2 + kstep;
;             if (last && has_next) S.a_ready(nxt);
;             if constexpr (has_mid<Epi>::value) { if (t == nh) E.mid(acc, cur, wr, wc, fr, fq); }
;             if constexpr (SP2) {
;             PG8_LDB(B0, 0, 0); PG8_LDB(B1, 0, 1); PG8_SCHED; PG8_LDA(At, 0, 0); PG8_STAGE(PG8_SA(1, 1), a1 + hstepA, voffA);
.LBB0_229:
	s_ashr_i32 s55, s54, 31
	s_lshl_b64 s[34:35], s[54:55], 21
	s_add_u32 s56, s58, s34
	s_addc_u32 s57, s59, s35
	s_and_b64 s[34:35], s[4:5], exec
	s_cselect_b32 s7, s57, s11
	s_cselect_b32 s9, s56, s10
	s_ashr_i32 s53, s52, 31
	s_lshl_b64 s[34:35], s[52:53], 21
	s_add_u32 s64, s3, s34
	s_addc_u32 s65, s74, s35
	s_and_b64 s[34:35], s[4:5], exec
	s_cselect_b32 s53, s65, s13
	s_cselect_b32 s55, s64, s12
	s_add_u32 s10, s10, 0x100080
	s_addc_u32 s11, s11, 0
	s_add_u32 s68, s12, 0x100
	v_mov_b32_e32 v0, 0
	s_addc_u32 s69, s13, 0
	s_mov_b32 s70, -2
	v_mov_b32_e32 v1, v0
	v_mov_b32_e32 v2, v0
	v_mov_b32_e32 v3, v0
	v_mov_b32_e32 v4, v0
	v_mov_b32_e32 v5, v0
	v_mov_b32_e32 v6, v0
	v_mov_b32_e32 v7, v0
	v_mov_b32_e32 v16, v0
	v_mov_b32_e32 v17, v0
	v_mov_b32_e32 v18, v0
	v_mov_b32_e32 v19, v0
	v_mov_b32_e32 v20, v0
	v_mov_b32_e32 v21, v0
	v_mov_b32_e32 v22, v0
	v_mov_b32_e32 v23, v0
	v_mov_b32_e32 v32, v0
	v_mov_b32_e32 v33, v0
	v_mov_b32_e32 v34, v0
	v_mov_b32_e32 v35, v0
	v_mov_b32_e32 v36, v0
	v_mov_b32_e32 v37, v0
	v_mov_b32_e32 v38, v0
	v_mov_b32_e32 v39, v0
	v_mov_b32_e32 v48, v0
	v_mov_b32_e32 v49, v0
	v_mov_b32_e32 v50, v0
	v_mov_b32_e32 v51, v0
	v_mov_b32_e32 v52, v0
	v_mov_b32_e32 v53, v0
	v_mov_b32_e32 v54, v0
	v_mov_b32_e32 v55, v0
	v_mov_b32_e32 v8, v0
	s_waitcnt lgkmcnt(0)
	v_mov_b32_e32 v9, v0
	v_mov_b32_e32 v10, v0
	v_mov_b32_e32 v11, v0
	v_mov_b32_e32 v12, v0
	v_mov_b32_e32 v13, v0
	v_mov_b32_e32 v14, v0
	v_mov_b32_e32 v15, v0
	v_mov_b32_e32 v24, v0
	v_mov_b32_e32 v25, v0
	v_mov_b32_e32 v26, v0
	v_mov_b32_e32 v27, v0
	v_mov_b32_e32 v28, v0
	v_mov_b32_e32 v29, v0
	v_mov_b32_e32 v30, v0
	v_mov_b32_e32 v31, v0
	v_mov_b32_e32 v40, v0
	v_mov_b32_e32 v41, v0
	v_mov_b32_e32 v42, v0
	v_mov_b32_e32 v43, v0
	v_mov_b32_e32 v44, v0
	v_mov_b32_e32 v45, v0
	v_mov_b32_e32 v46, v0
	v_mov_b32_e32 v47, v0
	v_mov_b32_e32 v56, v0
	v_mov_b32_e32 v57, v0
	v_mov_b32_e32 v58, v0
	v_mov_b32_e32 v59, v0
	v_mov_b32_e32 v60, v0
	v_mov_b32_e32 v61, v0
	v_mov_b32_e32 v62, v0
	v_mov_b32_e32 v63, v0
	v_mov_b32_e32 v64, v0
	v_mov_b32_e32 v65, v0
	v_mov_b32_e32 v66, v0
	v_mov_b32_e32 v67, v0
	v_mov_b32_e32 v68, v0
	v_mov_b32_e32 v69, v0
	v_mov_b32_e32 v70, v0
	v_mov_b32_e32 v71, v0
	v_mov_b32_e32 v80, v0
	v_mov_b32_e32 v81, v0
	v_mov_b32_e32 v82, v0
	v_mov_b32_e32 v83, v0
	v_mov_b32_e32 v84, v0
	v_mov_b32_e32 v85, v0
	v_mov_b32_e32 v86, v0
	v_mov_b32_e32 v87, v0
	v_mov_b32_e32 v96, v0
	v_mov_b32_e32 v97, v0
	v_mov_b32_e32 v98, v0
	v_mov_b32_e32 v99, v0
	v_mov_b32_e32 v100, v0
	v_mov_b32_e32 v101, v0
	v_mov_b32_e32 v102, v0
	v_mov_b32_e32 v103, v0
	v_mov_b32_e32 v112, v0
	v_mov_b32_e32 v113, v0
	v_mov_b32_e32 v114, v0
	v_mov_b32_e32 v115, v0
	v_mov_b32_e32 v116, v0
	v_mov_b32_e32 v117, v0
	v_mov_b32_e32 v118, v0
	v_mov_b32_e32 v119, v0
	v_mov_b32_e32 v72, v0
	v_mov_b32_e32 v73, v0
	v_mov_b32_e32 v74, v0
	v_mov_b32_e32 v75, v0
	v_mov_b32_e32 v76, v0
	v_mov_b32_e32 v77, v0
	v_mov_b32_e32 v78, v0
	v_mov_b32_e32 v79, v0
	v_mov_b32_e32 v88, v0
	v_mov_b32_e32 v89, v0
	v_mov_b32_e32 v90, v0
	v_mov_b32_e32 v91, v0
	v_mov_b32_e32 v92, v0
	v_mov_b32_e32 v93, v0
	v_mov_b32_e32 v94, v0
	v_mov_b32_e32 v95, v0
	v_mov_b32_e32 v104, v0
	v_mov_b32_e32 v105, v0
	v_mov_b32_e32 v106, v0
	v_mov_b32_e32 v107, v0
	v_mov_b32_e32 v108, v0
	v_mov_b32_e32 v109, v0
	v_mov_b32_e32 v110, v0
	v_mov_b32_e32 v111, v0
	v_mov_b32_e32 v120, v0
	v_mov_b32_e32 v121, v0
	v_mov_b32_e32 v122, v0
	v_mov_b32_e32 v123, v0
	v_mov_b32_e32 v124, v0
	v_mov_b32_e32 v125, v0
	v_mov_b32_e32 v126, v0
	v_mov_b32_e32 v127, v0
	v_add_u32_e32 v228, 0x18000, v153
	v_add_u32_e32 v229, 0x1c000, v153
.LBB0_230:
	ds_read_b128 v[146:149], v155
	ds_read_b128 v[160:163], v155 offset:1024
	ds_read_b128 v[164:167], v155 offset:2048
	ds_read_b128 v[168:171], v155 offset:3072
	ds_read_b128 v[172:175], v156
	ds_read_b128 v[176:179], v156 offset:1024
	ds_read_b128 v[180:183], v156 offset:2048
	ds_read_b128 v[184:187], v156 offset:3072
	s_add_u32 s12, s10, 0xfff00080
	s_addc_u32 s13, s11, -1
	s_cmp_eq_u32 s70, 60
	s_cselect_b32 s67, s7, s13
	s_cselect_b32 s66, s9, s12
	s_cselect_b32 s13, s53, s69
	s_cselect_b32 s12, s55, s68
	s_add_i32 m0, s76, 0xc000
	ds_read_b128 v[188:191], v157
	ds_read_b128 v[192:195], v157 offset:1024
	ds_read_b128 v[196:199], v157 offset:2048
	ds_read_b128 v[200:203], v157 offset:3072
	ds_read_b128 v[204:207], v157 offset:4096
	ds_read_b128 v[208:211], v157 offset:5120
	ds_read_b128 v[212:215], v157 offset:6144
	ds_read_b128 v[216:219], v157 offset:7168
	global_load_lds_dwordx4 v138, s[10:11]
	s_add_i32 m0, s76, 0xe000
	s_nop 0
	global_load_lds_dwordx4 v140, s[10:11]
	s_waitcnt vmcnt(8)
	s_waitcnt lgkmcnt(0)
	s_barrier
; #define PG8_STAGE(bufoff, gbase, voff) do { _Pragma("unroll") for (int _i = 0; _i < 2; ++_i) \
;         __builtin_amdgcn_global_load_lds((const unsigned*)((const char*)(gbase) + (voff)[_i]), (LAS unsigned*)(lds + (bufoff) + ldsw + _i * 8192), 16, 0, 0); } while (0)
; #define PG8_LDA(dst, b, h) do { _Pragma("unroll") for (int m = 0; m < 4; ++m) _Pragma("unroll") for (int k = 0; k < 2; ++k) dst[m][k] = *(const LAS bf16x8*)(lds + PG8_SA(b, h) + aoff + m * 2048 + k * 1024); } while (0)
; #define PG8_MMA(ai, bj, At, Bt) do { __builtin_amdgcn_s_setprio(1); _Pragma("unroll") for (int m = 0; m < 4; ++m) _Pragma("unroll") for (int n = 0; n < 2; ++n) _Pragma("unroll") for (int k = 0; k < 2; ++k) \
;         acc[ai][bj][m][n] = __builtin_amdgcn_mfma_f32_16x16x32_bf16(Bt[n][k], At[m][k], acc[ai][bj][m][n], 0, 0, 0); __builtin_amdgcn_s_setprio(0); } while (0)
; #define PG8_WAIT_V(n) asm volatile("s_waitcnt vmcnt(" #n ")" ::: "memory")
; #define PG8_WAIT_L(n) asm volatile("s_waitcnt lgkmcnt(" #n ")" ::: "memory")
; #define PG8_BAR __builtin_amdgcn_s_barrier()
; #define PG8_SCHED __builtin_amdgcn_sched_barrier(0)
; template <class Epi, class Sched, bool ALIGN_EPI = false, bool SP2 = false, bool TWOA = false, bool AGM = false>
; __device__ __forceinline__ void gemm_phase(LAS unsigned char* lds, const Gemm g, const Sched& S, const Epi& E, int wid) {
;     ...
;             PG8_WAIT_V(8); PG8_WAIT_L(0); PG8_BAR; PG8_MMA(0, 0, At, B0); PG8_MMA(0, 1, At, B1); PG8_BAR; PG8_SCHED;
;             PG8_LDA(At, 0, 1); PG8_STAGE(PG8_SB(0, 0), b2, voffB); PG8_STAGE(PG8_SB(0, 1), b2 + hstep, voffB); PG8_STAGE(PG8_SA(0, 0), a2, voffA);
;             PG8_WAIT_V(8); PG8_WAIT_L(0); PG8_BAR; PG8_MMA(1, 0, At, B0); PG8_MMA(1, 1, At, B1); PG8_BAR; PG8_SCHED;
	s_setprio 1
	s_waitcnt lgkmcnt(0)
	v_mfma_f32_16x16x32_bf16 v[124:127], v[146:149], v[188:191], v[124:127]
	v_mfma_f32_16x16x32_bf16 v[120:123], v[164:167], v[188:191], v[120:123]
	v_mfma_f32_16x16x32_bf16 v[108:111], v[146:149], v[196:199], v[108:111]
	v_mfma_f32_16x16x32_bf16 v[104:107], v[164:167], v[196:199], v[104:107]
	v_mfma_f32_16x16x32_bf16 v[92:95], v[146:149], v[204:207], v[92:95]
	v_mfma_f32_16x16x32_bf16 v[88:91], v[164:167], v[204:207], v[88:91]
	v_mfma_f32_16x16x32_bf16 v[76:79], v[146:149], v[212:215], v[76:79]
	v_mfma_f32_16x16x32_bf16 v[72:75], v[164:167], v[212:215], v[72:75]
	v_mfma_f32_16x16x32_bf16 v[124:127], v[160:163], v[192:195], v[124:127]
	v_mfma_f32_16x16x32_bf16 v[120:123], v[168:171], v[192:195], v[120:123]
	v_mfma_f32_16x16x32_bf16 v[108:111], v[160:163], v[200:203], v[108:111]
	v_mfma_f32_16x16x32_bf16 v[104:107], v[168:171], v[200:203], v[104:107]
	v_mfma_f32_16x16x32_bf16 v[92:95], v[160:163], v[208:211], v[92:95]
	v_mfma_f32_16x16x32_bf16 v[88:91], v[168:171], v[208:211], v[88:91]
	v_mfma_f32_16x16x32_bf16 v[76:79], v[160:163], v[216:219], v[76:79]
	v_mfma_f32_16x16x32_bf16 v[72:75], v[168:171], v[216:219], v[72:75]
	s_setprio 0
	s_setprio 1
	v_mfma_f32_16x16x32_bf16 v[116:119], v[172:175], v[188:191], v[116:119]
	v_mfma_f32_16x16x32_bf16 v[112:115], v[180:183], v[188:191], v[112:115]
	v_mfma_f32_16x16x32_bf16 v[100:103], v[172:175], v[196:199], v[100:103]
	v_mfma_f32_16x16x32_bf16 v[96:99], v[180:183], v[196:199], v[96:99]
	v_mfma_f32_16x16x32_bf16 v[84:87], v[172:175], v[204:207], v[84:87]
	v_mfma_f32_16x16x32_bf16 v[80:83], v[180:183], v[204:207], v[80:83]
	v_mfma_f32_16x16x32_bf16 v[68:71], v[172:175], v[212:215], v[68:71]
	v_mfma_f32_16x16x32_bf16 v[64:67], v[180:183], v[212:215], v[64:67]
	v_mfma_f32_16x16x32_bf16 v[116:119], v[176:179], v[192:195], v[116:119]
	v_mfma_f32_16x16x32_bf16 v[112:115], v[184:187], v[192:195], v[112:115]
	v_mfma_f32_16x16x32_bf16 v[100:103], v[176:179], v[200:203], v[100:103]
	v_mfma_f32_16x16x32_bf16 v[96:99], v[184:187], v[200:203], v[96:99]
	v_mfma_f32_16x16x32_bf16 v[84:87], v[176:179], v[208:211], v[84:87]
	v_mfma_f32_16x16x32_bf16 v[80:83], v[184:187], v[208:211], v[80:83]
	v_mfma_f32_16x16x32_bf16 v[68:71], v[176:179], v[216:219], v[68:71]
	v_mfma_f32_16x16x32_bf16 v[64:67], v[184:187], v[216:219], v[64:67]
	s_setprio 0
	s_barrier
	s_add_i32 s34, s95, s75
	s_mov_b32 m0, s34
	ds_read_b128 v[188:191], v157 offset:16384
	ds_read_b128 v[192:195], v157 offset:17408
	ds_read_b128 v[196:199], v157 offset:18432
	ds_read_b128 v[200:203], v157 offset:19456
	ds_read_b128 v[204:207], v157 offset:20480
	ds_read_b128 v[208:211], v157 offset:21504
	ds_read_b128 v[212:215], v157 offset:22528
	ds_read_b128 v[216:219], v157 offset:23552
	global_load_lds_dwordx4 v130, s[12:13]
	s_add_i32 m0, s34, 0x2000
	s_add_u32 s34, s12, 0x100000
	s_addc_u32 s35, s13, 0
	s_add_i32 s71, s96, s75
	global_load_lds_dwordx4 v134, s[12:13]
	s_mov_b32 m0, s71
	s_nop 0
	global_load_lds_dwordx4 v130, s[34:35]
	s_add_i32 m0, s71, 0x2000
	s_nop 0
	global_load_lds_dwordx4 v134, s[34:35]
	s_mov_b32 m0, s76
	s_nop 0
	global_load_lds_dwordx4 v128, s[66:67]
	s_mov_b32 m0, s77
	s_nop 0
	global_load_lds_dwordx4 v132, s[66:67]
	s_waitcnt vmcnt(8)
	s_waitcnt lgkmcnt(0)
	s_barrier
	s_setprio 1
	s_waitcnt lgkmcnt(0)
	v_mfma_f32_16x16x32_bf16 v[60:63], v[146:149], v[188:191], v[60:63]
	v_mfma_f32_16x16x32_bf16 v[56:59], v[164:167], v[188:191], v[56:59]
	v_mfma_f32_16x16x32_bf16 v[44:47], v[146:149], v[196:199], v[44:47]
	v_mfma_f32_16x16x32_bf16 v[40:43], v[164:167], v[196:199], v[40:43]
	v_mfma_f32_16x16x32_bf16 v[28:31], v[146:149], v[204:207], v[28:31]
	v_mfma_f32_16x16x32_bf16 v[24:27], v[164:167], v[204:207], v[24:27]
	v_mfma_f32_16x16x32_bf16 v[12:15], v[146:149], v[212:215], v[12:15]
	v_mfma_f32_16x16x32_bf16 v[8:11], v[164:167], v[212:215], v[8:11]
	v_mfma_f32_16x16x32_bf16 v[60:63], v[160:163], v[192:195], v[60:63]
	v_mfma_f32_16x16x32_bf16 v[56:59], v[168:171], v[192:195], v[56:59]
	v_mfma_f32_16x16x32_bf16 v[44:47], v[160:163], v[200:203], v[44:47]
	v_mfma_f32_16x16x32_bf16 v[40:43], v[168:171], v[200:203], v[40:43]
	v_mfma_f32_16x16x32_bf16 v[28:31], v[160:163], v[208:211], v[28:31]
	v_mfma_f32_16x16x32_bf16 v[24:27], v[168:171], v[208:211], v[24:27]
	v_mfma_f32_16x16x32_bf16 v[12:15], v[160:163], v[216:219], v[12:15]
	v_mfma_f32_16x16x32_bf16 v[8:11], v[168:171], v[216:219], v[8:11]
	s_setprio 0
	s_setprio 1
	v_mfma_f32_16x16x32_bf16 v[52:55], v[172:175], v[188:191], v[52:55]
	v_mfma_f32_16x16x32_bf16 v[48:51], v[180:183], v[188:191], v[48:51]
	v_mfma_f32_16x16x32_bf16 v[36:39], v[172:175], v[196:199], v[36:39]
	v_mfma_f32_16x16x32_bf16 v[32:35], v[180:183], v[196:199], v[32:35]
	v_mfma_f32_16x16x32_bf16 v[20:23], v[172:175], v[204:207], v[20:23]
	v_mfma_f32_16x16x32_bf16 v[16:19], v[180:183], v[204:207], v[16:19]
	v_mfma_f32_16x16x32_bf16 v[4:7], v[172:175], v[212:215], v[4:7]
	v_mfma_f32_16x16x32_bf16 v[0:3], v[180:183], v[212:215], v[0:3]
	v_mfma_f32_16x16x32_bf16 v[52:55], v[176:179], v[192:195], v[52:55]
	v_mfma_f32_16x16x32_bf16 v[48:51], v[184:187], v[192:195], v[48:51]
	v_mfma_f32_16x16x32_bf16 v[36:39], v[176:179], v[200:203], v[36:39]
	v_mfma_f32_16x16x32_bf16 v[32:35], v[184:187], v[200:203], v[32:35]
	v_mfma_f32_16x16x32_bf16 v[20:23], v[176:179], v[208:211], v[20:23]
	v_mfma_f32_16x16x32_bf16 v[16:19], v[184:187], v[208:211], v[16:19]
	v_mfma_f32_16x16x32_bf16 v[4:7], v[176:179], v[216:219], v[4:7]
	v_mfma_f32_16x16x32_bf16 v[0:3], v[184:187], v[216:219], v[0:3]
	s_setprio 0
	s_barrier
; #define PG8_STAGE(bufoff, gbase, voff) do { _Pragma("unroll") for (int _i = 0; _i < 2; ++_i) \
;         __builtin_amdgcn_global_load_lds((const unsigned*)((const char*)(gbase) + (voff)[_i]), (LAS unsigned*)(lds + (bufoff) + ldsw + _i * 8192), 16, 0, 0); } while (0)
; #define PG8_LDA(dst, b, h) do { _Pragma("unroll") for (int m = 0; m < 4; ++m) _Pragma("unroll") for (int k = 0; k < 2; ++k) dst[m][k] = *(const LAS bf16x8*)(lds + PG8_SA(b, h) + aoff + m * 2048 + k * 1024); } while (0)
; #define PG8_LDB(dst, b, h) do { _Pragma("unroll") for (int n = 0; n < 2; ++n) _Pragma("unroll") for (int k = 0; k < 2; ++k) dst[n][k] = *(const LAS bf16x8*)(lds + PG8_SB(b, h) + boff + n * 2048 + k * 1024); } while (0)
; #define PG8_MMA(ai, bj, At, Bt) do { __builtin_amdgcn_s_setprio(1); _Pragma("unroll") for (int m = 0; m < 4; ++m) _Pragma("unroll") for (int n = 0; n < 2; ++n) _Pragma("unroll") for (int k = 0; k < 2; ++k) \
;         acc[ai][bj][m][n] = __builtin_amdgcn_mfma_f32_16x16x32_bf16(Bt[n][k], At[m][k], acc[ai][bj][m][n], 0, 0, 0); __builtin_amdgcn_s_setprio(0); } while (0)
; #define PG8_WAIT_V(n) asm volatile("s_waitcnt vmcnt(" #n ")" ::: "memory")
; #define PG8_WAIT_L(n) asm volatile("s_waitcnt lgkmcnt(" #n ")" ::: "memory")
; #define PG8_BAR __builtin_amdgcn_s_barrier()
; #define PG8_SCHED __builtin_amdgcn_sched_barrier(0)
; template <class Epi, class Sched, bool ALIGN_EPI = false, bool SP2 = false, bool TWOA = false, bool AGM = false>
; __device__ __forceinline__ void gemm_phase(LAS unsigned char* lds, const Gemm g, const Sched& S, const Epi& E, int wid) {
;     ...
;             PG8_LDB(B0, 1, 0); PG8_LDB(B1, 1, 1); PG8_SCHED; PG8_LDA(At, 1, 0); PG8_STAGE(PG8_SA(0, 1), a2 + hstepA, voffA);
;             PG8_WAIT_V(8); PG8_WAIT_L(0); PG8_BAR; PG8_MMA(0, 0, At, B0); PG8_MMA(0, 1, At, B1); PG8_BAR; PG8_SCHED;
;             PG8_LDA(At, 1, 1); PG8_STAGE(PG8_SB(1, 0), b3, voffB); PG8_STAGE(PG8_SB(1, 1), b3 + hstep, voffB); PG8_STAGE(PG8_SA(1, 0), a3, voffA);
;             PG8_WAIT_V(8); PG8_WAIT_L(0); PG8_BAR; PG8_MMA(1, 0, At, B0); PG8_MMA(1, 1, At, B1); PG8_BAR; PG8_SCHED;
	s_add_i32 s71, 0, 0x18000
	s_add_i32 s72, 0, 0x1c000
	ds_read_b128 v[146:149], v228
	ds_read_b128 v[160:163], v228 offset:1024
	ds_read_b128 v[164:167], v228 offset:2048
	ds_read_b128 v[168:171], v228 offset:3072
	ds_read_b128 v[172:175], v229
	ds_read_b128 v[176:179], v229 offset:1024
	ds_read_b128 v[180:183], v229 offset:2048
	ds_read_b128 v[184:187], v229 offset:3072
	s_add_u32 s34, s66, 0x100000
	s_addc_u32 s35, s67, 0
	s_mov_b32 m0, s81
	ds_read_b128 v[188:191], v157 offset:32768
	ds_read_b128 v[192:195], v157 offset:33792
	ds_read_b128 v[196:199], v157 offset:34816
	ds_read_b128 v[200:203], v157 offset:35840
	ds_read_b128 v[204:207], v157 offset:36864
	ds_read_b128 v[208:211], v157 offset:37888
	ds_read_b128 v[212:215], v157 offset:38912
	ds_read_b128 v[216:219], v157 offset:39936
	global_load_lds_dwordx4 v128, s[34:35]
	s_mov_b32 m0, s82
	s_nop 0
	global_load_lds_dwordx4 v132, s[34:35]
	s_waitcnt vmcnt(8)
	s_waitcnt lgkmcnt(0)
	s_barrier
	s_setprio 1
	s_waitcnt lgkmcnt(0)
	v_mfma_f32_16x16x32_bf16 v[124:127], v[146:149], v[188:191], v[124:127]
	v_mfma_f32_16x16x32_bf16 v[120:123], v[164:167], v[188:191], v[120:123]
	v_mfma_f32_16x16x32_bf16 v[108:111], v[146:149], v[196:199], v[108:111]
	v_mfma_f32_16x16x32_bf16 v[104:107], v[164:167], v[196:199], v[104:107]
	v_mfma_f32_16x16x32_bf16 v[92:95], v[146:149], v[204:207], v[92:95]
	v_mfma_f32_16x16x32_bf16 v[88:91], v[164:167], v[204:207], v[88:91]
	v_mfma_f32_16x16x32_bf16 v[76:79], v[146:149], v[212:215], v[76:79]
	v_mfma_f32_16x16x32_bf16 v[72:75], v[164:167], v[212:215], v[72:75]
	v_mfma_f32_16x16x32_bf16 v[124:127], v[160:163], v[192:195], v[124:127]
	v_mfma_f32_16x16x32_bf16 v[120:123], v[168:171], v[192:195], v[120:123]
	v_mfma_f32_16x16x32_bf16 v[108:111], v[160:163], v[200:203], v[108:111]
	v_mfma_f32_16x16x32_bf16 v[104:107], v[168:171], v[200:203], v[104:107]
	v_mfma_f32_16x16x32_bf16 v[92:95], v[160:163], v[208:211], v[92:95]
	v_mfma_f32_16x16x32_bf16 v[88:91], v[168:171], v[208:211], v[88:91]
	v_mfma_f32_16x16x32_bf16 v[76:79], v[160:163], v[216:219], v[76:79]
	v_mfma_f32_16x16x32_bf16 v[72:75], v[168:171], v[216:219], v[72:75]
	s_setprio 0
	s_setprio 1
	v_mfma_f32_16x16x32_bf16 v[116:119], v[172:175], v[188:191], v[116:119]
	v_mfma_f32_16x16x32_bf16 v[112:115], v[180:183], v[188:191], v[112:115]
	v_mfma_f32_16x16x32_bf16 v[100:103], v[172:175], v[196:199], v[100:103]
	v_mfma_f32_16x16x32_bf16 v[96:99], v[180:183], v[196:199], v[96:99]
	v_mfma_f32_16x16x32_bf16 v[84:87], v[172:175], v[204:207], v[84:87]
	v_mfma_f32_16x16x32_bf16 v[80:83], v[180:183], v[204:207], v[80:83]
	v_mfma_f32_16x16x32_bf16 v[68:71], v[172:175], v[212:215], v[68:71]
	v_mfma_f32_16x16x32_bf16 v[64:67], v[180:183], v[212:215], v[64:67]
	v_mfma_f32_16x16x32_bf16 v[116:119], v[176:179], v[192:195], v[116:119]
	v_mfma_f32_16x16x32_bf16 v[112:115], v[184:187], v[192:195], v[112:115]
	v_mfma_f32_16x16x32_bf16 v[100:103], v[176:179], v[200:203], v[100:103]
	v_mfma_f32_16x16x32_bf16 v[96:99], v[184:187], v[200:203], v[96:99]
	v_mfma_f32_16x16x32_bf16 v[84:87], v[176:179], v[208:211], v[84:87]
	v_mfma_f32_16x16x32_bf16 v[80:83], v[184:187], v[208:211], v[80:83]
	v_mfma_f32_16x16x32_bf16 v[68:71], v[176:179], v[216:219], v[68:71]
	v_mfma_f32_16x16x32_bf16 v[64:67], v[184:187], v[216:219], v[64:67]
	s_setprio 0
	s_barrier
	s_add_i32 s34, s71, s75
	s_add_u32 s98, s12, s46
	s_addc_u32 s99, s13, s47
	s_mov_b32 m0, s34
	ds_read_b128 v[188:191], v157 offset:49152
	ds_read_b128 v[192:195], v157 offset:50176
	ds_read_b128 v[196:199], v157 offset:51200
	ds_read_b128 v[200:203], v157 offset:52224
	ds_read_b128 v[204:207], v157 offset:53248
	ds_read_b128 v[208:211], v157 offset:54272
	ds_read_b128 v[212:215], v157 offset:55296
	ds_read_b128 v[216:219], v157 offset:56320
	global_load_lds_dwordx4 v130, s[98:99]
	s_add_i32 m0, s34, 0x2000
	s_add_u32 s12, s12, 0x100080
	s_addc_u32 s13, s13, 0
	s_add_i32 s34, s72, s75
	global_load_lds_dwordx4 v134, s[98:99]
	s_mov_b32 m0, s34
	s_nop 0
	global_load_lds_dwordx4 v130, s[12:13]
	s_add_i32 m0, s34, 0x2000
	s_nop 0
	global_load_lds_dwordx4 v134, s[12:13]
	s_add_u32 s100, s66, s46
	s_addc_u32 s101, s67, s47
	s_mov_b32 m0, s88
	s_nop 0
	global_load_lds_dwordx4 v128, s[100:101]
	s_mov_b32 m0, s89
	s_nop 0
	global_load_lds_dwordx4 v132, s[100:101]
	s_waitcnt vmcnt(8)
	s_waitcnt lgkmcnt(0)
	s_barrier
	s_setprio 1
	s_waitcnt lgkmcnt(0)
	v_mfma_f32_16x16x32_bf16 v[60:63], v[146:149], v[188:191], v[60:63]
	v_mfma_f32_16x16x32_bf16 v[56:59], v[164:167], v[188:191], v[56:59]
	v_mfma_f32_16x16x32_bf16 v[44:47], v[146:149], v[196:199], v[44:47]
	v_mfma_f32_16x16x32_bf16 v[40:43], v[164:167], v[196:199], v[40:43]
	v_mfma_f32_16x16x32_bf16 v[28:31], v[146:149], v[204:207], v[28:31]
	v_mfma_f32_16x16x32_bf16 v[24:27], v[164:167], v[204:207], v[24:27]
	v_mfma_f32_16x16x32_bf16 v[12:15], v[146:149], v[212:215], v[12:15]
	v_mfma_f32_16x16x32_bf16 v[8:11], v[164:167], v[212:215], v[8:11]
	v_mfma_f32_16x16x32_bf16 v[60:63], v[160:163], v[192:195], v[60:63]
	v_mfma_f32_16x16x32_bf16 v[56:59], v[168:171], v[192:195], v[56:59]
	v_mfma_f32_16x16x32_bf16 v[44:47], v[160:163], v[200:203], v[44:47]
	v_mfma_f32_16x16x32_bf16 v[40:43], v[168:171], v[200:203], v[40:43]
	v_mfma_f32_16x16x32_bf16 v[28:31], v[160:163], v[208:211], v[28:31]
	v_mfma_f32_16x16x32_bf16 v[24:27], v[168:171], v[208:211], v[24:27]
	v_mfma_f32_16x16x32_bf16 v[12:15], v[160:163], v[216:219], v[12:15]
	v_mfma_f32_16x16x32_bf16 v[8:11], v[168:171], v[216:219], v[8:11]
	s_setprio 0
	s_setprio 1
	v_mfma_f32_16x16x32_bf16 v[52:55], v[172:175], v[188:191], v[52:55]
	v_mfma_f32_16x16x32_bf16 v[48:51], v[180:183], v[188:191], v[48:51]
	v_mfma_f32_16x16x32_bf16 v[36:39], v[172:175], v[196:199], v[36:39]
	v_mfma_f32_16x16x32_bf16 v[32:35], v[180:183], v[196:199], v[32:35]
	v_mfma_f32_16x16x32_bf16 v[20:23], v[172:175], v[204:207], v[20:23]
	v_mfma_f32_16x16x32_bf16 v[16:19], v[180:183], v[204:207], v[16:19]
	v_mfma_f32_16x16x32_bf16 v[4:7], v[172:175], v[212:215], v[4:7]
	v_mfma_f32_16x16x32_bf16 v[0:3], v[180:183], v[212:215], v[0:3]
	v_mfma_f32_16x16x32_bf16 v[52:55], v[176:179], v[192:195], v[52:55]
	v_mfma_f32_16x16x32_bf16 v[48:51], v[184:187], v[192:195], v[48:51]
	v_mfma_f32_16x16x32_bf16 v[36:39], v[176:179], v[200:203], v[36:39]
	v_mfma_f32_16x16x32_bf16 v[32:35], v[184:187], v[200:203], v[32:35]
	v_mfma_f32_16x16x32_bf16 v[20:23], v[176:179], v[208:211], v[20:23]
	v_mfma_f32_16x16x32_bf16 v[16:19], v[184:187], v[208:211], v[16:19]
	v_mfma_f32_16x16x32_bf16 v[4:7], v[176:179], v[216:219], v[4:7]
	v_mfma_f32_16x16x32_bf16 v[0:3], v[184:187], v[216:219], v[0:3]
	s_setprio 0
	s_barrier
	s_add_i32 s70, s70, 2
	s_add_u32 s10, s10, 0x100
	s_addc_u32 s11, s11, 0
	s_add_u32 s68, s68, 0x100
	s_addc_u32 s69, s69, 0
	s_cmp_gt_u32 s70, 61
	s_cbranch_scc0 .LBB0_230
	s_and_b64 vcc, exec, s[50:51]
	s_cbranch_vccz .LBB0_233
	s_barrier
